# GLU phase part 1 (D*u + y_fwd + y_bwd, gelu, bf16 LDS tile): 16 serialized load-compute steps rewritten as 4 batches of 16 loads with counted waits
# speedup vs baseline: 1.0119x; 1.0005x over previous
.LBB0_831:
	s_ashr_i32 s41, s40, 31
	s_and_b64 vcc, exec, s[34:35]
	s_cbranch_vccz .LBB0_814
	v_mov_b32_e32 v76, v188
	s_movk_i32 s0, 0x210
	v_ashrrev_i32_e32 v2, 2, v76
	v_and_b32_e32 v3, 3, v76
	v_mul_lo_u32 v0, v2, s0
	v_lshlrev_b32_e32 v8, 3, v3
	v_add3_u32 v16, v0, v8, 0
	v_lshlrev_b32_e32 v0, 4, v3
	v_ashrrev_i32_e32 v3, 31, v2
	v_lshl_add_u64 v[2:3], v[2:3], 0, s[40:41]
	v_lshlrev_b64 v[4:5], 6, v[2:3]
	v_lshl_add_u64 v[6:7], s[94:95], 0, v[4:5]
	v_mad_u64_u32 v[4:5], s[0:1], v2, s59, 0
	v_mad_i32_i24 v3, v3, s59, v5
	v_or_b32_e32 v2, v4, v8
	v_lshl_add_u64 v[8:9], s[30:31], 0, v[2:3]
	s_mov_b32 s2, 0
	s_mov_b64 s[34:35], s[10:11]
	v_ashrrev_i32_e32 v246, 2, v76
	v_and_b32_e32 v247, 3, v76
	v_add_u32_e32 v246, s40, v246
	v_lshlrev_b32_e32 v248, 6, v246
	v_lshl_add_u32 v248, v247, 4, v248
	v_mul_u32_u24_e32 v249, 0xa00, v246
	v_lshl_add_u32 v249, v247, 3, v249
	v_lshlrev_b32_e32 v250, 4, v247
	s_add_u32 s98, s94, 0xbd00000
	s_addc_u32 s99, s95, 0
	s_add_u32 s100, s98, 0x1200000
	s_addc_u32 s101, s99, 0
	v_mov_b32_e32 v255, v16
.Lglu_b:
	global_load_dwordx4 v[2:5], v248, s[98:99]
	global_load_dwordx4 v[18:21], v248, s[100:101]
	global_load_dwordx4 v[226:229], v250, s[34:35] offset:-204
	global_load_dwordx2 v[14:15], v249, s[30:31] offset:-64
	s_add_u32 s98, s98, 0x120000
	s_addc_u32 s99, s99, 0
	s_add_u32 s100, s100, 0x120000
	s_addc_u32 s101, s101, 0
	global_load_dwordx4 v[6:9], v248, s[98:99]
	global_load_dwordx4 v[22:25], v248, s[100:101]
	global_load_dwordx4 v[230:233], v250, s[34:35] offset:-140
	global_load_dwordx2 v[26:27], v249, s[30:31] offset:-32
	s_add_u32 s98, s98, 0x120000
	s_addc_u32 s99, s99, 0
	s_add_u32 s100, s100, 0x120000
	s_addc_u32 s101, s101, 0
	global_load_dwordx4 v[10:13], v248, s[98:99]
	global_load_dwordx4 v[218:221], v248, s[100:101]
	global_load_dwordx4 v[234:237], v250, s[34:35] offset:-76
	global_load_dwordx2 v[242:243], v249, s[30:31] offset:0
	s_add_u32 s98, s98, 0x120000
	s_addc_u32 s99, s99, 0
	s_add_u32 s100, s100, 0x120000
	s_addc_u32 s101, s101, 0
	global_load_dwordx4 v[214:217], v248, s[98:99]
	global_load_dwordx4 v[222:225], v248, s[100:101]
	global_load_dwordx4 v[238:241], v250, s[34:35] offset:-12
	global_load_dwordx2 v[244:245], v249, s[30:31] offset:32
	s_add_u32 s98, s98, 0x120000
	s_addc_u32 s99, s99, 0
	s_add_u32 s100, s100, 0x120000
	s_addc_u32 s101, s101, 0
	s_waitcnt vmcnt(12)
	v_lshlrev_b32_e32 v17, 16, v14
	v_and_b32_e32 v246, 0xffff0000, v14
	v_fma_f32 v2, v226, v17, v2
	v_fma_f32 v3, v227, v246, v3
	v_lshlrev_b32_e32 v17, 16, v15
	v_and_b32_e32 v246, 0xffff0000, v15
	v_fma_f32 v4, v228, v17, v4
	v_fma_f32 v5, v229, v246, v5
	v_add_f32_e32 v2, v18, v2
	v_add_f32_e32 v3, v19, v3
	v_add_f32_e32 v4, v20, v4
	v_add_f32_e32 v5, v21, v5
	v_mul_f32_e32 v17, 0x3d372713, v2
	v_mul_f32_e32 v246, 0x3d372713, v3
	v_mul_f32_e32 v247, 0x3d372713, v4
	v_mul_f32_e32 v226, 0x3d372713, v5
	v_mul_f32_e32 v17, v2, v17
	v_mul_f32_e32 v246, v3, v246
	v_mul_f32_e32 v247, v4, v247
	v_mul_f32_e32 v226, v5, v226
	v_fma_f32 v17, v2, v17, v2
	v_fma_f32 v246, v3, v246, v3
	v_fma_f32 v247, v4, v247, v4
	v_fma_f32 v226, v5, v226, v5
	v_mul_f32_e32 v17, 0x3f4c422a, v17
	v_mul_f32_e32 v246, 0x3f4c422a, v246
	v_mul_f32_e32 v247, 0x3f4c422a, v247
	v_mul_f32_e32 v226, 0x3f4c422a, v226
	v_add_f32_e32 v17, v17, v17
	v_add_f32_e32 v246, v246, v246
	v_add_f32_e32 v247, v247, v247
	v_add_f32_e32 v226, v226, v226
	v_mul_f32_e32 v17, 0x3fb8aa3b, v17
	v_mul_f32_e32 v246, 0x3fb8aa3b, v246
	v_mul_f32_e32 v247, 0x3fb8aa3b, v247
	v_mul_f32_e32 v226, 0x3fb8aa3b, v226
	v_exp_f32_e32 v17, v17
	v_exp_f32_e32 v246, v246
	v_exp_f32_e32 v247, v247
	v_exp_f32_e32 v226, v226
	v_mul_f32_e32 v2, 0.5, v2
	v_mul_f32_e32 v3, 0.5, v3
	v_mul_f32_e32 v4, 0.5, v4
	v_mul_f32_e32 v5, 0.5, v5
	v_add_f32_e32 v17, 1.0, v17
	v_add_f32_e32 v246, 1.0, v246
	v_add_f32_e32 v247, 1.0, v247
	v_add_f32_e32 v226, 1.0, v226
	v_rcp_f32_e32 v17, v17
	v_rcp_f32_e32 v246, v246
	v_rcp_f32_e32 v247, v247
	v_rcp_f32_e32 v226, v226
	v_fma_f32 v17, v17, -2.0, 1.0
	v_fma_f32 v246, v246, -2.0, 1.0
	v_fma_f32 v247, v247, -2.0, 1.0
	v_fma_f32 v226, v226, -2.0, 1.0
	v_add_f32_e32 v17, 1.0, v17
	v_add_f32_e32 v246, 1.0, v246
	v_add_f32_e32 v247, 1.0, v247
	v_add_f32_e32 v226, 1.0, v226
	v_mul_f32_e32 v2, v2, v17
	v_mul_f32_e32 v3, v3, v246
	v_mul_f32_e32 v4, v4, v247
	v_mul_f32_e32 v5, v5, v226
	v_cvt_pk_bf16_f32 v28, v2, v3
	v_cvt_pk_bf16_f32 v29, v4, v5
	ds_write_b64 v255, v[28:29]
	s_waitcnt vmcnt(8)
	v_lshlrev_b32_e32 v17, 16, v26
	v_and_b32_e32 v246, 0xffff0000, v26
	v_fma_f32 v6, v230, v17, v6
	v_fma_f32 v7, v231, v246, v7
	v_lshlrev_b32_e32 v17, 16, v27
	v_and_b32_e32 v246, 0xffff0000, v27
	v_fma_f32 v8, v232, v17, v8
	v_fma_f32 v9, v233, v246, v9
	v_add_f32_e32 v6, v22, v6
	v_add_f32_e32 v7, v23, v7
	v_add_f32_e32 v8, v24, v8
	v_add_f32_e32 v9, v25, v9
	v_mul_f32_e32 v17, 0x3d372713, v6
	v_mul_f32_e32 v246, 0x3d372713, v7
	v_mul_f32_e32 v247, 0x3d372713, v8
	v_mul_f32_e32 v230, 0x3d372713, v9
	v_mul_f32_e32 v17, v6, v17
	v_mul_f32_e32 v246, v7, v246
	v_mul_f32_e32 v247, v8, v247
	v_mul_f32_e32 v230, v9, v230
	v_fma_f32 v17, v6, v17, v6
	v_fma_f32 v246, v7, v246, v7
	v_fma_f32 v247, v8, v247, v8
	v_fma_f32 v230, v9, v230, v9
	v_mul_f32_e32 v17, 0x3f4c422a, v17
	v_mul_f32_e32 v246, 0x3f4c422a, v246
	v_mul_f32_e32 v247, 0x3f4c422a, v247
	v_mul_f32_e32 v230, 0x3f4c422a, v230
	v_add_f32_e32 v17, v17, v17
	v_add_f32_e32 v246, v246, v246
	v_add_f32_e32 v247, v247, v247
	v_add_f32_e32 v230, v230, v230
	v_mul_f32_e32 v17, 0x3fb8aa3b, v17
	v_mul_f32_e32 v246, 0x3fb8aa3b, v246
	v_mul_f32_e32 v247, 0x3fb8aa3b, v247
	v_mul_f32_e32 v230, 0x3fb8aa3b, v230
	v_exp_f32_e32 v17, v17
	v_exp_f32_e32 v246, v246
	v_exp_f32_e32 v247, v247
	v_exp_f32_e32 v230, v230
	v_mul_f32_e32 v6, 0.5, v6
	v_mul_f32_e32 v7, 0.5, v7
	v_mul_f32_e32 v8, 0.5, v8
	v_mul_f32_e32 v9, 0.5, v9
	v_add_f32_e32 v17, 1.0, v17
	v_add_f32_e32 v246, 1.0, v246
	v_add_f32_e32 v247, 1.0, v247
	v_add_f32_e32 v230, 1.0, v230
	v_rcp_f32_e32 v17, v17
	v_rcp_f32_e32 v246, v246
	v_rcp_f32_e32 v247, v247
	v_rcp_f32_e32 v230, v230
	v_fma_f32 v17, v17, -2.0, 1.0
	v_fma_f32 v246, v246, -2.0, 1.0
	v_fma_f32 v247, v247, -2.0, 1.0
	v_fma_f32 v230, v230, -2.0, 1.0
	v_add_f32_e32 v17, 1.0, v17
	v_add_f32_e32 v246, 1.0, v246
	v_add_f32_e32 v247, 1.0, v247
	v_add_f32_e32 v230, 1.0, v230
	v_mul_f32_e32 v6, v6, v17
	v_mul_f32_e32 v7, v7, v246
	v_mul_f32_e32 v8, v8, v247
	v_mul_f32_e32 v9, v9, v230
	v_cvt_pk_bf16_f32 v28, v6, v7
	v_cvt_pk_bf16_f32 v29, v8, v9
	ds_write_b64 v255, v[28:29] offset:32
	s_waitcnt vmcnt(4)
	v_lshlrev_b32_e32 v17, 16, v242
	v_and_b32_e32 v246, 0xffff0000, v242
	v_fma_f32 v10, v234, v17, v10
	v_fma_f32 v11, v235, v246, v11
	v_lshlrev_b32_e32 v17, 16, v243
	v_and_b32_e32 v246, 0xffff0000, v243
	v_fma_f32 v12, v236, v17, v12
	v_fma_f32 v13, v237, v246, v13
	v_add_f32_e32 v10, v218, v10
	v_add_f32_e32 v11, v219, v11
	v_add_f32_e32 v12, v220, v12
	v_add_f32_e32 v13, v221, v13
	v_mul_f32_e32 v17, 0x3d372713, v10
	v_mul_f32_e32 v246, 0x3d372713, v11
	v_mul_f32_e32 v247, 0x3d372713, v12
	v_mul_f32_e32 v234, 0x3d372713, v13
	v_mul_f32_e32 v17, v10, v17
	v_mul_f32_e32 v246, v11, v246
	v_mul_f32_e32 v247, v12, v247
	v_mul_f32_e32 v234, v13, v234
	v_fma_f32 v17, v10, v17, v10
	v_fma_f32 v246, v11, v246, v11
	v_fma_f32 v247, v12, v247, v12
	v_fma_f32 v234, v13, v234, v13
	v_mul_f32_e32 v17, 0x3f4c422a, v17
	v_mul_f32_e32 v246, 0x3f4c422a, v246
	v_mul_f32_e32 v247, 0x3f4c422a, v247
	v_mul_f32_e32 v234, 0x3f4c422a, v234
	v_add_f32_e32 v17, v17, v17
	v_add_f32_e32 v246, v246, v246
	v_add_f32_e32 v247, v247, v247
	v_add_f32_e32 v234, v234, v234
	v_mul_f32_e32 v17, 0x3fb8aa3b, v17
	v_mul_f32_e32 v246, 0x3fb8aa3b, v246
	v_mul_f32_e32 v247, 0x3fb8aa3b, v247
	v_mul_f32_e32 v234, 0x3fb8aa3b, v234
	v_exp_f32_e32 v17, v17
	v_exp_f32_e32 v246, v246
	v_exp_f32_e32 v247, v247
	v_exp_f32_e32 v234, v234
	v_mul_f32_e32 v10, 0.5, v10
	v_mul_f32_e32 v11, 0.5, v11
	v_mul_f32_e32 v12, 0.5, v12
	v_mul_f32_e32 v13, 0.5, v13
	v_add_f32_e32 v17, 1.0, v17
	v_add_f32_e32 v246, 1.0, v246
	v_add_f32_e32 v247, 1.0, v247
	v_add_f32_e32 v234, 1.0, v234
	v_rcp_f32_e32 v17, v17
	v_rcp_f32_e32 v246, v246
	v_rcp_f32_e32 v247, v247
	v_rcp_f32_e32 v234, v234
	v_fma_f32 v17, v17, -2.0, 1.0
	v_fma_f32 v246, v246, -2.0, 1.0
	v_fma_f32 v247, v247, -2.0, 1.0
	v_fma_f32 v234, v234, -2.0, 1.0
	v_add_f32_e32 v17, 1.0, v17
	v_add_f32_e32 v246, 1.0, v246
	v_add_f32_e32 v247, 1.0, v247
	v_add_f32_e32 v234, 1.0, v234
	v_mul_f32_e32 v10, v10, v17
	v_mul_f32_e32 v11, v11, v246
	v_mul_f32_e32 v12, v12, v247
	v_mul_f32_e32 v13, v13, v234
	v_cvt_pk_bf16_f32 v28, v10, v11
	v_cvt_pk_bf16_f32 v29, v12, v13
	ds_write_b64 v255, v[28:29] offset:64
	s_waitcnt vmcnt(0)
	v_lshlrev_b32_e32 v17, 16, v244
	v_and_b32_e32 v246, 0xffff0000, v244
	v_fma_f32 v214, v238, v17, v214
	v_fma_f32 v215, v239, v246, v215
	v_lshlrev_b32_e32 v17, 16, v245
	v_and_b32_e32 v246, 0xffff0000, v245
	v_fma_f32 v216, v240, v17, v216
	v_fma_f32 v217, v241, v246, v217
	v_add_f32_e32 v214, v222, v214
	v_add_f32_e32 v215, v223, v215
	v_add_f32_e32 v216, v224, v216
	v_add_f32_e32 v217, v225, v217
	v_mul_f32_e32 v17, 0x3d372713, v214
	v_mul_f32_e32 v246, 0x3d372713, v215
	v_mul_f32_e32 v247, 0x3d372713, v216
	v_mul_f32_e32 v238, 0x3d372713, v217
	v_mul_f32_e32 v17, v214, v17
	v_mul_f32_e32 v246, v215, v246
	v_mul_f32_e32 v247, v216, v247
	v_mul_f32_e32 v238, v217, v238
	v_fma_f32 v17, v214, v17, v214
	v_fma_f32 v246, v215, v246, v215
	v_fma_f32 v247, v216, v247, v216
	v_fma_f32 v238, v217, v238, v217
	v_mul_f32_e32 v17, 0x3f4c422a, v17
	v_mul_f32_e32 v246, 0x3f4c422a, v246
	v_mul_f32_e32 v247, 0x3f4c422a, v247
	v_mul_f32_e32 v238, 0x3f4c422a, v238
	v_add_f32_e32 v17, v17, v17
	v_add_f32_e32 v246, v246, v246
	v_add_f32_e32 v247, v247, v247
	v_add_f32_e32 v238, v238, v238
	v_mul_f32_e32 v17, 0x3fb8aa3b, v17
	v_mul_f32_e32 v246, 0x3fb8aa3b, v246
	v_mul_f32_e32 v247, 0x3fb8aa3b, v247
	v_mul_f32_e32 v238, 0x3fb8aa3b, v238
	v_exp_f32_e32 v17, v17
	v_exp_f32_e32 v246, v246
	v_exp_f32_e32 v247, v247
	v_exp_f32_e32 v238, v238
	v_mul_f32_e32 v214, 0.5, v214
	v_mul_f32_e32 v215, 0.5, v215
	v_mul_f32_e32 v216, 0.5, v216
	v_mul_f32_e32 v217, 0.5, v217
	v_add_f32_e32 v17, 1.0, v17
	v_add_f32_e32 v246, 1.0, v246
	v_add_f32_e32 v247, 1.0, v247
	v_add_f32_e32 v238, 1.0, v238
	v_rcp_f32_e32 v17, v17
	v_rcp_f32_e32 v246, v246
	v_rcp_f32_e32 v247, v247
	v_rcp_f32_e32 v238, v238
	v_fma_f32 v17, v17, -2.0, 1.0
	v_fma_f32 v246, v246, -2.0, 1.0
	v_fma_f32 v247, v247, -2.0, 1.0
	v_fma_f32 v238, v238, -2.0, 1.0
	v_add_f32_e32 v17, 1.0, v17
	v_add_f32_e32 v246, 1.0, v246
	v_add_f32_e32 v247, 1.0, v247
	v_add_f32_e32 v238, 1.0, v238
	v_mul_f32_e32 v214, v214, v17
	v_mul_f32_e32 v215, v215, v246
	v_mul_f32_e32 v216, v216, v247
	v_mul_f32_e32 v217, v217, v238
	v_cvt_pk_bf16_f32 v28, v214, v215
	v_cvt_pk_bf16_f32 v29, v216, v217
	ds_write_b64 v255, v[28:29] offset:96
	s_add_u32 s34, s34, 0x100
	s_addc_u32 s35, s35, 0
	v_add_u32_e32 v249, 0x80, v249
	v_add_u32_e32 v255, 0x80, v255
	s_add_u32 s2, s2, 1
	s_cmp_lt_u32 s2, 4
	s_cbranch_scc1 .Lglu_b
	v_and_b32_e32 v2, 0xffffffcf, v76
	v_bfe_u32 v78, v76, 4, 2
	v_ashrrev_i32_e32 v3, 31, v2
	v_and_b32_e32 v77, 15, v76
	v_lshlrev_b64 v[2:3], 9, v[2:3]
	v_lshlrev_b32_e32 v4, 4, v78
	v_readlane_b32 s0, v253, 11
	v_mul_u32_u24_e32 v0, 0x210, v77
	v_or_b32_e32 v2, v2, v4
	v_readlane_b32 s1, v253, 12
	v_mov_b32_e32 v34, 0
	v_add3_u32 v79, v0, v4, 0
	v_lshl_add_u64 v[66:67], s[0:1], 0, v[2:3]
	s_mov_b64 s[34:35], 0
	v_mov_b32_e32 v35, v34
	v_mov_b32_e32 v36, v34
	v_mov_b32_e32 v37, v34
	v_mov_b32_e32 v38, v34
	v_mov_b32_e32 v39, v34
	v_mov_b32_e32 v40, v34
	v_mov_b32_e32 v41, v34
	v_mov_b32_e32 v42, v34
	v_mov_b32_e32 v43, v34
	v_mov_b32_e32 v44, v34
	v_mov_b32_e32 v45, v34
	v_mov_b32_e32 v46, v34
	v_mov_b32_e32 v47, v34
	v_mov_b32_e32 v48, v34
	v_mov_b32_e32 v49, v34
	v_mov_b32_e32 v50, v34
	v_mov_b32_e32 v51, v34
	v_mov_b32_e32 v52, v34
	v_mov_b32_e32 v53, v34
	v_mov_b32_e32 v54, v34
	v_mov_b32_e32 v55, v34
	v_mov_b32_e32 v56, v34
	v_mov_b32_e32 v57, v34
	v_mov_b32_e32 v58, v34
	v_mov_b32_e32 v59, v34
	v_mov_b32_e32 v60, v34
	v_mov_b32_e32 v61, v34
	v_mov_b32_e32 v62, v34
	v_mov_b32_e32 v63, v34
	v_mov_b32_e32 v64, v34
	v_mov_b32_e32 v65, v34
	v_mov_b32_e32 v30, v34
	v_mov_b32_e32 v31, v34
	v_mov_b32_e32 v32, v34
	v_mov_b32_e32 v33, v34
	v_mov_b32_e32 v26, v34
	v_mov_b32_e32 v27, v34
	v_mov_b32_e32 v28, v34
	v_mov_b32_e32 v29, v34
	v_mov_b32_e32 v22, v34
	v_mov_b32_e32 v23, v34
	v_mov_b32_e32 v24, v34
	v_mov_b32_e32 v25, v34
	v_mov_b32_e32 v18, v34
	v_mov_b32_e32 v19, v34
	v_mov_b32_e32 v20, v34
	v_mov_b32_e32 v21, v34
	v_mov_b32_e32 v14, v34
	v_mov_b32_e32 v15, v34
	v_mov_b32_e32 v16, v34
	v_mov_b32_e32 v17, v34
	v_mov_b32_e32 v10, v34
	v_mov_b32_e32 v11, v34
	v_mov_b32_e32 v12, v34
	v_mov_b32_e32 v13, v34
	v_mov_b32_e32 v6, v34
	v_mov_b32_e32 v7, v34
	v_mov_b32_e32 v8, v34
	v_mov_b32_e32 v9, v34
	v_mov_b32_e32 v2, v34
	v_mov_b32_e32 v3, v34
	v_mov_b32_e32 v4, v34
	v_mov_b32_e32 v5, v34
	s_waitcnt lgkmcnt(0)
	s_barrier
